# hgrn_c next-unit prefetch no longer waited at issue (compact saddr loads, pair packing moved to iteration end)
# speedup vs baseline: 1.0070x; 1.0033x over previous
; __device__ __forceinline__ void hgrn_c_load(Ctx& X, int u, RawC& R) {
;     const int hd = u & 7, c = u >> 3, t0 = c * 64, seg = X.tid >> 7, k = X.tid & 127;
;     const bf16_t* PR = (const bf16_t*)(X.ws + WS_PROJ);
;     const bf16_t* HQ = PR + 3 * TSZ; const bf16_t* HLF = PR + 4 * TSZ; const bf16_t* HV = PR + 5 * TSZ;
; #pragma unroll
;     for (int i = 0; i < 16; ++i) { const size_t off = (size_t)(t0 + 16 * seg + i) * 1024 + hd * 128 + k; R.lf[i] = HLF[off]; R.q[i] = HQ[off]; R.vv[i] = HV[off]; }
; }
; __global__ void __launch_bounds__(512, 2) fwd_mega(Args a) {
;     ...
;         RawC cur; hgrn_c_load(X, blockIdx.x, cur);
.LBB0_727:
	s_cmp_lt_i32 s92, 6
	s_cselect_b64 s[2:3], -1, 0
	s_and_b64 s[12:13], s[2:3], s[0:1]
	s_andn2_b64 vcc, exec, s[12:13]
	s_cbranch_vccnz .LBB0_739
	v_readlane_b32 s0, v245, 0
	s_cmpk_gt_i32 s0, 0x7ff
	v_readlane_b32 s1, v245, 1
	s_cbranch_scc1 .LBB0_739
	s_add_u32 s14, s90, 0x11700000
	s_addc_u32 s15, s91, 0
	s_add_u32 s16, s90, 0x13700000
	s_addc_u32 s17, s91, 0
	s_add_u32 s18, s90, 0x15700000
	v_lshrrev_b32_e32 v70, 3, v209
	s_addc_u32 s19, s91, 0
	v_and_b32_e32 v71, 0x70, v70
	s_and_b32 s0, s54, 0xffffffc0
	v_readlane_b32 s34, v245, 0
	v_add_u32_e32 v0, s0, v71
	s_lshl_b32 s36, s34, 7
	v_and_b32_e32 v59, 0x7f, v209
	v_or_b32_e32 v2, 8, v0
	s_and_b32 s0, s36, 0x380
	v_or_b32_e32 v22, 13, v0
	v_or_b32_e32 v26, 14, v0
	v_ashrrev_i32_e32 v3, 31, v2
	v_or_b32_e32 v1, s0, v59
	v_or_b32_e32 v6, 9, v0
	v_or_b32_e32 v10, 10, v0
	v_or_b32_e32 v12, 11, v0
	v_or_b32_e32 v14, 12, v0
	v_ashrrev_i32_e32 v23, 31, v22
	v_ashrrev_i32_e32 v27, 31, v26
	v_or_b32_e32 v30, 15, v0
	v_lshlrev_b64 v[2:3], 11, v[2:3]
	v_lshlrev_b32_e32 v38, 1, v1
	v_ashrrev_i32_e32 v7, 31, v6
	v_ashrrev_i32_e32 v11, 31, v10
	v_ashrrev_i32_e32 v13, 31, v12
	v_ashrrev_i32_e32 v15, 31, v14
	v_lshlrev_b64 v[22:23], 11, v[22:23]
	v_lshlrev_b64 v[26:27], 11, v[26:27]
	v_ashrrev_i32_e32 v31, 31, v30
	v_or_b32_e32 v2, v2, v38
	v_lshlrev_b64 v[6:7], 11, v[6:7]
	v_lshlrev_b64 v[16:17], 11, v[10:11]
	v_lshlrev_b64 v[18:19], 11, v[12:13]
	v_lshlrev_b64 v[14:15], 11, v[14:15]
	v_or_b32_e32 v22, v22, v38
	v_or_b32_e32 v26, v26, v38
	v_lshlrev_b64 v[30:31], 11, v[30:31]
	v_lshl_add_u64 v[4:5], s[18:19], 0, v[2:3]
	v_or_b32_e32 v6, v6, v38
	v_or_b32_e32 v16, v16, v38
	v_or_b32_e32 v18, v18, v38
	v_or_b32_e32 v14, v14, v38
	v_lshl_add_u64 v[24:25], s[18:19], 0, v[22:23]
	v_lshl_add_u64 v[28:29], s[18:19], 0, v[26:27]
	v_or_b32_e32 v30, v30, v38
	v_lshl_add_u64 v[8:9], s[18:19], 0, v[6:7]
	v_lshl_add_u64 v[10:11], s[18:19], 0, v[16:17]
	v_lshl_add_u64 v[12:13], s[18:19], 0, v[18:19]
	v_lshl_add_u64 v[20:21], s[18:19], 0, v[14:15]
	v_lshl_add_u64 v[32:33], s[18:19], 0, v[30:31]
	global_load_ushort v40, v[4:5], off
	global_load_ushort v41, v[8:9], off
	global_load_ushort v42, v[10:11], off
	global_load_ushort v43, v[12:13], off
	global_load_ushort v44, v[20:21], off
	global_load_ushort v45, v[24:25], off
	global_load_ushort v46, v[28:29], off
	global_load_ushort v47, v[32:33], off
	v_lshl_add_u64 v[4:5], s[14:15], 0, v[30:31]
	v_lshl_add_u64 v[24:25], s[14:15], 0, v[26:27]
	v_lshl_add_u64 v[28:29], s[14:15], 0, v[22:23]
	v_lshl_add_u64 v[22:23], s[16:17], 0, v[22:23]
	v_lshl_add_u64 v[20:21], s[16:17], 0, v[30:31]
	v_lshl_add_u64 v[26:27], s[16:17], 0, v[26:27]
	v_lshl_add_u64 v[30:31], s[14:15], 0, v[14:15]
	v_lshl_add_u64 v[32:33], s[16:17], 0, v[14:15]
	global_load_ushort v12, v[4:5], off
	global_load_ushort v8, v[20:21], off
	global_load_ushort v13, v[24:25], off
	global_load_ushort v9, v[26:27], off
	global_load_ushort v14, v[28:29], off
	global_load_ushort v10, v[22:23], off
	global_load_ushort v15, v[30:31], off
	global_load_ushort v11, v[32:33], off
	v_lshl_add_u64 v[4:5], s[14:15], 0, v[18:19]
	v_lshl_add_u64 v[18:19], s[16:17], 0, v[18:19]
	v_lshl_add_u64 v[22:23], s[14:15], 0, v[6:7]
	v_lshl_add_u64 v[6:7], s[16:17], 0, v[6:7]
	v_lshl_add_u64 v[24:25], s[14:15], 0, v[2:3]
	v_lshl_add_u64 v[2:3], s[16:17], 0, v[2:3]
	v_ashrrev_i32_e32 v1, 31, v0
	v_lshl_add_u64 v[20:21], s[14:15], 0, v[16:17]
	v_lshl_add_u64 v[16:17], s[16:17], 0, v[16:17]
	global_load_ushort v121, v[4:5], off
	global_load_ushort v152, v[18:19], off
	global_load_ushort v115, v[20:21], off
	global_load_ushort v154, v[16:17], off
	global_load_ushort v119, v[22:23], off
	global_load_ushort v155, v[6:7], off
	global_load_ushort v132, v[24:25], off
	global_load_ushort v156, v[2:3], off
	v_lshlrev_b64 v[2:3], 11, v[0:1]
	v_or_b32_e32 v6, 1, v0
	v_or_b32_e32 v18, 2, v0
	v_or_b32_e32 v22, 3, v0
	v_or_b32_e32 v26, 4, v0
	v_or_b32_e32 v30, 5, v0
	v_or_b32_e32 v34, 6, v0
	v_or_b32_e32 v0, 7, v0
	v_ashrrev_i32_e32 v7, 31, v6
	v_ashrrev_i32_e32 v19, 31, v18
	v_ashrrev_i32_e32 v23, 31, v22
	v_ashrrev_i32_e32 v27, 31, v26
	v_ashrrev_i32_e32 v31, 31, v30
	v_ashrrev_i32_e32 v35, 31, v34
	v_ashrrev_i32_e32 v1, 31, v0
	v_or_b32_e32 v2, v2, v38
	v_lshlrev_b64 v[6:7], 11, v[6:7]
	v_lshlrev_b64 v[18:19], 11, v[18:19]
	v_lshlrev_b64 v[22:23], 11, v[22:23]
	v_lshlrev_b64 v[26:27], 11, v[26:27]
	v_lshlrev_b64 v[30:31], 11, v[30:31]
	v_lshlrev_b64 v[34:35], 11, v[34:35]
	v_lshlrev_b64 v[0:1], 11, v[0:1]
	v_lshl_add_u64 v[4:5], s[18:19], 0, v[2:3]
	v_or_b32_e32 v6, v6, v38
	v_or_b32_e32 v18, v18, v38
	v_or_b32_e32 v22, v22, v38
	v_or_b32_e32 v26, v26, v38
	v_or_b32_e32 v30, v30, v38
	v_or_b32_e32 v34, v34, v38
	v_or_b32_e32 v0, v0, v38
	v_lshl_add_u64 v[16:17], s[18:19], 0, v[6:7]
	v_lshl_add_u64 v[20:21], s[18:19], 0, v[18:19]
	v_lshl_add_u64 v[24:25], s[18:19], 0, v[22:23]
	v_lshl_add_u64 v[28:29], s[18:19], 0, v[26:27]
	v_lshl_add_u64 v[32:33], s[18:19], 0, v[30:31]
	v_lshl_add_u64 v[36:37], s[18:19], 0, v[34:35]
	v_lshl_add_u64 v[38:39], s[18:19], 0, v[0:1]
	global_load_ushort v48, v[4:5], off
	global_load_ushort v49, v[16:17], off
	global_load_ushort v50, v[20:21], off
	global_load_ushort v51, v[24:25], off
	global_load_ushort v52, v[28:29], off
	global_load_ushort v53, v[32:33], off
	global_load_ushort v54, v[36:37], off
	global_load_ushort v55, v[38:39], off
	v_lshl_add_u64 v[4:5], s[14:15], 0, v[0:1]
	v_lshl_add_u64 v[0:1], s[16:17], 0, v[0:1]
	v_lshl_add_u64 v[16:17], s[14:15], 0, v[34:35]
	v_lshl_add_u64 v[20:21], s[16:17], 0, v[34:35]
	v_lshl_add_u64 v[24:25], s[14:15], 0, v[30:31]
; __device__ __forceinline__ void hgrn_c_load(Ctx& X, int u, RawC& R) {
;     const int hd = u & 7, c = u >> 3, t0 = c * 64, seg = X.tid >> 7, k = X.tid & 127;
;     const bf16_t* PR = (const bf16_t*)(X.ws + WS_PROJ);
;     const bf16_t* HQ = PR + 3 * TSZ; const bf16_t* HLF = PR + 4 * TSZ; const bf16_t* HV = PR + 5 * TSZ;
; #pragma unroll
;     for (int i = 0; i < 16; ++i) { const size_t off = (size_t)(t0 + 16 * seg + i) * 1024 + hd * 128 + k; R.lf[i] = HLF[off]; R.q[i] = HQ[off]; R.vv[i] = HV[off]; }
; }
; __device__ __forceinline__ void hgrn_c_compute(Ctx& X, int u, const RawC& R) {
;     const int hd = u & 7, c = u >> 3, t0 = c * 64;
;     const int tid = X.tid, seg = tid >> 7, k = tid & 127, lane = X.lane, w = X.wave, r = lane & 31, h = lane >> 5;
;     LAS bf16_t* QH = (LAS bf16_t*)(X.lds);
;     LAS bf16_t* QT = (LAS bf16_t*)(X.lds + 17408);
;     LAS bf16_t* KT2 = (LAS bf16_t*)(X.lds + 34816);
;     LAS bf16_t* VT = (LAS bf16_t*)(X.lds + 52224);
;     LAS bf16_t* AM = (LAS bf16_t*)(X.lds + 70656);
;     LAS float* OF = (LAS float*)(X.lds + 79872);
;     LAS float* SEG = (LAS float*)(X.lds + 113664);
;     const bf16_t* HG = (const bf16_t*)(X.ws + WS_PROJ) + 6 * TSZ;
;     const int tt2 = w & 1, vt2 = w >> 1;
;     bf16x8 sfr[8];
;     {
;         const bf16_t* sb = (const bf16_t*)(X.ws + WS_SBUF) + (size_t)u * 16384 + (32 * vt2 + r) * 128 + 8 * h;
; #pragma unroll
;         for (int kk = 0; kk < 8; ++kk) sfr[kk] = *(const bf16x8*)(sb + 16 * kk);
;     }
;     const int tn = tid >> 3, sub = tid & 7;
;     const u32x4 g0 = *(const u32x4*)(HG + (size_t)(t0 + tn) * 1024 + hd * 128 + 16 * sub), g1 = *(const u32x4*)(HG + (size_t)(t0 + tn) * 1024 + hd * 128 + 16 * sub + 8);
;     {
;         float lf[16], b[16]; float run = 0.f;
; #pragma unroll
;         for (int i = 0; i < 16; ++i) { lf[i] = bf2f(R.lf[i]); run += lf[i]; b[i] = run; }
;         SEG[seg * 128 + k] = run;
;         __syncthreads();
;         float off = 0.f;
; #pragma unroll
;         for (int s = 0; s < 4; ++s) { const float v = SEG[s * 128 + k]; off += (s < seg) ? v : 0.f; }
;         const float bmid = SEG[k] + SEG[128 + k];
;         unsigned pv[8];
; #pragma unroll
;         for (int i = 0; i < 16; ++i) {
;             const float bt = off + b[i]; const int t = 16 * seg + i; const float q = bf2f(R.q[i]);
;             const unsigned qh = pk2_rne(q * __expf(bt), q * __expf(bt - bmid));
	v_lshl_add_u64 v[28:29], s[16:17], 0, v[30:31]
	v_lshl_add_u64 v[30:31], s[14:15], 0, v[26:27]
	v_lshl_add_u64 v[26:27], s[16:17], 0, v[26:27]
	global_load_ushort v149, v[4:5], off
	global_load_ushort v162, v[0:1], off
	global_load_ushort v150, v[16:17], off
	global_load_ushort v163, v[20:21], off
	global_load_ushort v151, v[24:25], off
	global_load_ushort v160, v[28:29], off
	global_load_ushort v153, v[30:31], off
	global_load_ushort v161, v[26:27], off
	v_lshl_add_u64 v[0:1], s[14:15], 0, v[22:23]
	v_lshl_add_u64 v[4:5], s[16:17], 0, v[22:23]
	v_lshl_add_u64 v[16:17], s[14:15], 0, v[18:19]
	v_lshl_add_u64 v[18:19], s[16:17], 0, v[18:19]
	v_lshl_add_u64 v[20:21], s[14:15], 0, v[6:7]
	v_lshl_add_u64 v[6:7], s[16:17], 0, v[6:7]
	v_lshl_add_u64 v[22:23], s[14:15], 0, v[2:3]
	v_lshl_add_u64 v[2:3], s[16:17], 0, v[2:3]
	global_load_ushort v157, v[0:1], off
	global_load_ushort v165, v[4:5], off
	global_load_ushort v158, v[16:17], off
	global_load_ushort v166, v[18:19], off
	global_load_ushort v159, v[20:21], off
	global_load_ushort v167, v[6:7], off
	global_load_ushort v164, v[22:23], off
	global_load_ushort v168, v[2:3], off
	s_add_u32 s20, s90, 0x17700000
	v_readlane_b32 s30, v245, 21
	s_addc_u32 s21, s91, 0
	s_lshr_b32 s22, s30, 7
	s_movk_i32 s2, 0xff
	s_lshl_b32 s28, s22, 5
	s_add_i32 s0, 0, 0x1bc00
	v_cmp_lt_u32_e64 s[4:5], s2, v209
	s_movk_i32 s2, 0x17f
	v_cmp_lt_u32_e64 s[6:7], s2, v209
	s_movk_i32 s2, 0x1ff
	s_cmpk_lt_u32 s30, 0x100
	v_cmp_lt_u32_e64 s[8:9], s2, v209
	s_cselect_b64 s[24:25], -1, 0
	s_lshr_b32 s2, s30, 1
	s_and_b32 s37, s2, 32
	s_cmp_lg_u32 s22, 1
	v_lshrrev_b32_e32 v0, 7, v209
	v_lshrrev_b32_e32 v1, 5, v208
	v_lshlrev_b32_e32 v3, 4, v209
	s_cselect_b64 s[2:3], -1, 0
	s_bitcmp1_b32 s30, 6
	v_and_b32_e32 v72, 31, v209
	v_and_b32_e32 v16, 0x70, v3
	v_mul_u32_u24_e32 v3, 0x880, v0
	v_lshlrev_b32_e32 v20, 5, v0
	s_cselect_b64 s[10:11], -1, 0
	v_lshlrev_b32_e32 v0, 4, v1
	v_or_b32_e32 v2, s28, v72
	s_or_b64 s[26:27], s[2:3], s[10:11]
	v_add_u32_e32 v58, 0, v0
	s_movk_i32 s10, 0x110
	v_mad_u64_u32 v[60:61], s[2:3], v2, s10, v[58:59]
	s_add_i32 s2, 0, 0x11400
	s_lshl_b32 s3, s22, 6
	s_movk_i32 s29, 0x90
	s_add_i32 s3, s2, s3
	v_lshl_add_u32 v81, v1, 3, s3
	v_add_u32_e32 v96, s2, v0
	v_mad_u64_u32 v[62:63], s[2:3], v2, s29, v[58:59]
	s_add_i32 s3, 0, 0x13800
	v_mul_u32_u24_e32 v0, 0x210, v70
	v_lshlrev_b32_e32 v56, 2, v16
	v_add3_u32 v97, s3, v0, v56
	v_mbcnt_lo_u32_b32 v0, -1, 0
	v_mbcnt_hi_u32_b32 v0, -1, v0
	v_and_b32_e32 v2, 64, v0
	v_lshlrev_b32_e32 v78, 2, v1
	v_xor_b32_e32 v1, 1, v0
	v_add_u32_e32 v2, 64, v2
	v_readlane_b32 s35, v245, 1
	s_and_b32 s2, s30, 0xffffff80
	v_cmp_lt_i32_e32 vcc, v1, v2
	s_add_i32 s2, s3, s2
	v_readlane_b32 s56, v245, 5
	v_cndmask_b32_e32 v1, v0, v1, vcc
	s_ashr_i32 s35, s34, 31
	v_and_b32_e32 v18, 32, v209
	v_mov_b32_e32 v57, 0
	v_lshl_add_u32 v63, v72, 2, s2
	v_lshlrev_b32_e32 v98, 2, v1
	v_xor_b32_e32 v1, 2, v0
	v_readlane_b32 s57, v245, 6
	s_lshl_b64 s[2:3], s[34:35], 15
	v_lshrrev_b32_e32 v18, 1, v18
	v_lshlrev_b32_e32 v21, 7, v72
	v_cmp_lt_i32_e32 vcc, v1, v2
	v_lshl_add_u64 v[64:65], s[56:57], 0, v[56:57]
	v_or_b32_e32 v18, s2, v18
	v_mov_b32_e32 v19, s3
	v_lshl_or_b32 v56, s22, 12, v21
	v_cndmask_b32_e32 v1, v0, v1, vcc
	v_lshl_add_u64 v[18:19], v[56:57], 1, v[18:19]
	v_lshlrev_b32_e32 v99, 2, v1
	v_xor_b32_e32 v1, 4, v0
	v_lshl_add_u64 v[18:19], s[90:91], 0, v[18:19]
	s_mov_b64 s[2:3], 0xb700080
	v_cmp_lt_i32_e32 vcc, v1, v2
	v_lshl_add_u64 v[66:67], v[18:19], 0, s[2:3]
	s_ashr_i32 s3, s94, 31
	s_mov_b32 s2, s94
	v_lshl_add_u32 v73, v209, 2, s0
	v_lshl_add_u32 v74, v59, 2, s0
	s_movk_i32 s0, 0x80
	v_or_b32_e32 v3, v3, v59
	v_mad_u32_u24 v17, v59, s29, 0
	v_or_b32_e32 v76, s37, v72
	v_or_b32_e32 v80, s28, v78
	v_cndmask_b32_e32 v0, v0, v1, vcc
	s_mov_b32 s39, 0x5040100
	s_lshl_b64 s[28:29], s[2:3], 15
	s_mov_b32 s3, 0x800000
	s_mov_b32 s2, s34
	s_mov_b32 s23, 0
	v_cmp_gt_u32_e64 s[0:1], s0, v209
	v_lshl_add_u32 v75, v3, 1, 0
	v_mul_u32_u24_e32 v77, 0x90, v76
	v_mul_u32_u24_e32 v61, 0x110, v76
	v_mad_u32_u24 v79, v76, s10, v58
	v_or_b32_e32 v82, 2, v80
	v_or_b32_e32 v83, 3, v80
	v_or_b32_e32 v84, 8, v80
	v_or_b32_e32 v85, 9, v80
	v_or_b32_e32 v86, 10, v80
	v_or_b32_e32 v87, 11, v80
	v_or_b32_e32 v88, 16, v80
	v_or_b32_e32 v89, 17, v80
	v_or_b32_e32 v90, 18, v80
	v_or_b32_e32 v91, 19, v80
	v_or_b32_e32 v92, 24, v80
	v_or_b32_e32 v93, 25, v80
	v_or_b32_e32 v94, 26, v80
	v_or_b32_e32 v95, 27, v80
	s_movk_i32 s38, 0x210
	v_lshlrev_b32_e32 v100, 2, v0
	v_readlane_b32 s58, v245, 7
	v_readlane_b32 s59, v245, 8
	v_readlane_b32 s60, v245, 9
	v_readlane_b32 s61, v245, 10
	v_readlane_b32 s62, v245, 11
	v_readlane_b32 s63, v245, 12
	v_readlane_b32 s64, v245, 13
	v_readlane_b32 s65, v245, 14
	v_readlane_b32 s66, v245, 15
	v_readlane_b32 s67, v245, 16
	v_readlane_b32 s68, v245, 17
	v_readlane_b32 s69, v245, 18
	v_readlane_b32 s70, v245, 19
	v_readlane_b32 s71, v245, 20
	v_mul_u32_u24_e32 v101, 0x90, v72
	v_mul_u32_u24_e32 v102, 0x110, v72
	s_waitcnt vmcnt(22)
	v_perm_b32 v0, v49, v48, s39
	s_waitcnt vmcnt(20)
	v_perm_b32 v1, v51, v50, s39
	s_waitcnt vmcnt(18)
	v_perm_b32 v2, v53, v52, s39
	s_waitcnt vmcnt(16)
	v_perm_b32 v3, v55, v54, s39
	v_perm_b32 v4, v41, v40, s39
	v_perm_b32 v5, v43, v42, s39
	v_perm_b32 v6, v45, v44, s39
	v_perm_b32 v7, v47, v46, s39
	s_lshl_b32 s40, s94, 7
	v_lshlrev_b32_e32 v56, 1, v16
	v_add_u32_e32 v103, v17, v20
	v_mov_b32_e32 v104, 0x358637bd
	s_mov_b64 s[30:31], 0x7700800
	s_mov_b32 s41, 0x7700000
	v_writelane_b32 v245, s2, 0
	s_mov_b32 s42, s34
	s_nop 0
	v_writelane_b32 v245, s3, 1
	s_waitcnt vmcnt(0)
	s_branch .LBB0_733

; #define LAS __attribute__((address_space(3)))
; __device__ __forceinline__ int crow(int reg, int h) { return (reg & 3) + 8 * (reg >> 2) + 4 * h; }
; #define MFMA32(a, b, c) __builtin_amdgcn_mfma_f32_32x32x16_bf16((a), (b), (c), 0, 0, 0)
; __device__ __forceinline__ void hgrn_c_compute(Ctx& X, int u, const RawC& R) {
;     ...
;     {
;         f32x16 acc;
; #pragma unroll
;         for (int i = 0; i < 16; ++i) acc[i] = 0.f;
; #pragma unroll
;         for (int kk = 0; kk < 8; ++kk) {
;             const bf16x8 af = *(const LAS bf16x8*)(QH + (32 * tt2 + r) * 136 + 16 * kk + 8 * h);
;             acc = MFMA32(af, sfr[kk], acc);
;         }
; #pragma unroll
;         for (int ks = 0; ks < 4; ++ks) {
;             const bf16x8 af = *(const LAS bf16x8*)(AM + (32 * tt2 + r) * 72 + 16 * ks + 8 * h);
;             const bf16x8 bfr = *(const LAS bf16x8*)(VT + (32 * vt2 + r) * 72 + 16 * ks + 8 * h);
;             acc = MFMA32(af, bfr, acc);
;         }
; #pragma unroll
;         for (int i = 0; i < 16; ++i) OF[(32 * tt2 + crow(i, h)) * 132 + 32 * vt2 + r] = acc[i];
;     }
;     __syncthreads();
.LBB0_732:
	v_add_u32_e32 v119, v58, v119
	s_waitcnt lgkmcnt(0)
	s_barrier
	ds_read_b128 v[0:3], v119
	ds_read_b128 v[150:153], v119 offset:32
	s_waitcnt vmcnt(9) lgkmcnt(1)
	v_mfma_f32_32x32x16_bf16 v[0:15], v[0:3], v[52:55], 0
	v_add_u32_e32 v115, v96, v115
	s_waitcnt vmcnt(1)
	v_lshlrev_b32_e32 v174, 16, v16
	v_and_b32_e32 v175, 0xffff0000, v16
	v_lshlrev_b32_e32 v176, 16, v19
	v_and_b32_e32 v177, 0xffff0000, v19
	v_add_u32_e32 v121, s2, v78
	s_waitcnt vmcnt(0)
	v_lshlrev_b32_e32 v170, 16, v28
	s_waitcnt lgkmcnt(0)
	v_mfma_f32_32x32x16_bf16 v[0:15], v[150:153], v[48:51], v[0:15]
	ds_read_b128 v[48:51], v119 offset:64
	ds_read_b128 v[52:55], v119 offset:96
	v_and_b32_e32 v171, 0xffff0000, v28
	v_lshlrev_b32_e32 v172, 16, v29
	v_and_b32_e32 v173, 0xffff0000, v29
	s_add_i32 s54, s54, s50
	s_add_i32 s36, s36, s40
	v_lshl_add_u64 v[66:67], v[66:67], 0, s[28:29]
	s_waitcnt lgkmcnt(1)
	v_mfma_f32_32x32x16_bf16 v[0:15], v[48:51], v[44:47], v[0:15]
	v_mov_b32_e32 v168, v114
	v_mov_b32_e32 v167, v112
	v_mov_b32_e32 v166, v113
	v_mov_b32_e32 v165, v122
	v_mov_b32_e32 v161, v123
	v_mov_b32_e32 v160, v124
	v_mov_b32_e32 v163, v128
	s_waitcnt lgkmcnt(0)
	v_mfma_f32_32x32x16_bf16 v[0:15], v[52:55], v[40:43], v[0:15]
	ds_read_b128 v[40:43], v119 offset:128
	ds_read_b128 v[44:47], v119 offset:160
	v_mov_b32_e32 v162, v129
	v_mov_b32_e32 v156, v137
	v_mov_b32_e32 v155, v138
	v_mov_b32_e32 v154, v139
	v_mov_b32_e32 v152, v148
	v_mov_b32_e32 v164, v105
	s_waitcnt lgkmcnt(1)
	v_mfma_f32_32x32x16_bf16 v[0:15], v[40:43], v[36:39], v[0:15]
	ds_read_b128 v[36:39], v62 offset:52224
	ds_read_b128 v[40:43], v62 offset:52256
	ds_read_b128 v[48:51], v119 offset:192
	v_mov_b32_e32 v159, v106
	v_mov_b32_e32 v158, v107
	v_mov_b32_e32 v157, v108
	v_mov_b32_e32 v153, v109
	v_mov_b32_e32 v151, v116
	v_mov_b32_e32 v150, v110
	s_waitcnt lgkmcnt(3)
	v_mfma_f32_32x32x16_bf16 v[0:15], v[44:47], v[32:35], v[0:15]
	ds_read_b128 v[32:35], v62 offset:52288
	ds_read_b128 v[44:47], v62 offset:52320
	ds_read_b128 v[52:55], v119 offset:224
	v_mov_b32_e32 v149, v111
	v_mov_b32_e32 v132, v118
	v_mov_b32_e32 v119, v120
	s_waitcnt lgkmcnt(3)
	v_mfma_f32_32x32x16_bf16 v[0:15], v[48:51], v[24:27], v[0:15]
	ds_read_b128 v[24:27], v115
	v_lshlrev_b32_e32 v48, 16, v30
	v_and_b32_e32 v49, 0xffff0000, v30
	v_lshlrev_b32_e32 v50, 16, v31
	v_and_b32_e32 v51, 0xffff0000, v31
	s_waitcnt lgkmcnt(1)
	v_mfma_f32_32x32x16_bf16 v[0:15], v[52:55], v[20:23], v[0:15]
	v_lshlrev_b32_e32 v52, 16, v17
	v_and_b32_e32 v53, 0xffff0000, v17
	v_lshlrev_b32_e32 v54, 16, v18
	v_and_b32_e32 v55, 0xffff0000, v18
	ds_read_b128 v[16:19], v115 offset:32
	ds_read_b128 v[20:23], v115 offset:64
	s_waitcnt lgkmcnt(2)
	v_mfma_f32_32x32x16_bf16 v[0:15], v[24:27], v[36:39], v[0:15]
	v_mad_i32_i24 v24, v121, s38, v63
	v_add_u32_e32 v25, 0x2400, v24
	v_add_u32_e32 v26, 0x3000, v24
	v_add_u32_e32 v27, 0x3400, v24
	v_lshlrev_b64 v[36:37], 12, v[68:69]
	v_lshl_add_u64 v[36:37], s[90:91], 0, v[36:37]
	v_lshl_add_u64 v[36:37], v[36:37], 0, s[22:23]
	s_waitcnt lgkmcnt(1)
	v_mfma_f32_32x32x16_bf16 v[0:15], v[16:19], v[40:43], v[0:15]
	ds_read_b128 v[16:19], v115 offset:96
	v_lshl_add_u64 v[36:37], v[36:37], 0, v[56:57]
	v_mov_b32_e32 v115, v117
	v_mov_b32_e32 v121, v131
	s_waitcnt lgkmcnt(1)
	v_mfma_f32_32x32x16_bf16 v[0:15], v[20:23], v[32:35], v[0:15]
	v_add_u32_e32 v20, 0x400, v24
	v_add_u32_e32 v21, 0x1000, v24
	v_add_u32_e32 v22, 0x1400, v24
	v_add_u32_e32 v23, 0x2000, v24
	s_waitcnt lgkmcnt(0)
	v_mfma_f32_32x32x16_bf16 v[0:15], v[16:19], v[44:47], v[0:15]
	s_nop 11
	ds_write2_b32 v24, v0, v1 offset1:132
	ds_write2_b32 v20, v2, v3 offset0:8 offset1:140
	ds_write2_b32 v21, v4, v5 offset0:32 offset1:164
	ds_write2_b32 v22, v6, v7 offset0:40 offset1:172
	ds_write2_b32 v23, v8, v9 offset0:64 offset1:196
	ds_write2_b32 v25, v10, v11 offset0:72 offset1:204
	ds_write2_b32 v26, v12, v13 offset0:96 offset1:228
	ds_write2_b32 v27, v14, v15 offset0:104 offset1:236
	s_waitcnt lgkmcnt(0)
	s_barrier
; #define LAS __attribute__((address_space(3)))
; __device__ __forceinline__ unsigned pk2_rne(float lo, float hi) { const f32x2_t f = {lo, hi}; return __builtin_bit_cast(unsigned, __builtin_convertvector(f, bf16x2_t)); }
; __device__ __forceinline__ float bflo(unsigned w) { return __uint_as_float(w << 16); }
; __device__ __forceinline__ float bfhi(unsigned w) { return __uint_as_float(w & 0xffff0000u); }
; __device__ __forceinline__ void hgrn_c_load(Ctx& X, int u, RawC& R) {
;     const int hd = u & 7, c = u >> 3, t0 = c * 64, seg = X.tid >> 7, k = X.tid & 127;
;     const bf16_t* PR = (const bf16_t*)(X.ws + WS_PROJ);
;     const bf16_t* HQ = PR + 3 * TSZ; const bf16_t* HLF = PR + 4 * TSZ; const bf16_t* HV = PR + 5 * TSZ;
; #pragma unroll
;     for (int i = 0; i < 16; ++i) { const size_t off = (size_t)(t0 + 16 * seg + i) * 1024 + hd * 128 + k; R.lf[i] = HLF[off]; R.q[i] = HQ[off]; R.vv[i] = HV[off]; }
; }
; __device__ __forceinline__ void hgrn_c_compute(Ctx& X, int u, const RawC& R) {
;     ...
;     {
;         float ov[16]; float ss = 0.f;
; #pragma unroll
;         for (int e = 0; e < 4; ++e) { const f32x4 q4 = *(const LAS f32x4*)(OF + tn * 132 + 16 * sub + 4 * e); ov[4 * e] = q4[0]; ov[4 * e + 1] = q4[1]; ov[4 * e + 2] = q4[2]; ov[4 * e + 3] = q4[3]; }
; #pragma unroll
;         for (int e = 0; e < 16; ++e) ss += ov[e] * ov[e];
;         ss += __shfl_xor(ss, 1); ss += __shfl_xor(ss, 2); ss += __shfl_xor(ss, 4);
;         const float rinv = rsqrtf(ss * (1.f / 128.f) + EPS);
;         const unsigned gw[8] = {g0.x, g0.y, g0.z, g0.w, g1.x, g1.y, g1.z, g1.w};
;         unsigned pw[8];
; #pragma unroll
;         for (int e = 0; e < 8; ++e) {
;             const float w0 = X.gnorm_w[16 * sub + 2 * e], w1 = X.gnorm_w[16 * sub + 2 * e + 1];
;             pw[e] = pk2_rne(ov[2 * e] * rinv * w0 * bflo(gw[e]), ov[2 * e + 1] * rinv * w1 * bfhi(gw[e]));
;         }
;         bf16_t* yp = (bf16_t*)(X.ws + WS_H) + (size_t)(t0 + tn) * D + 1024 + hd * 128 + 16 * sub;
;         *(u32x4*)(yp) = (u32x4){pw[0], pw[1], pw[2], pw[3]}; *(u32x4*)(yp + 8) = (u32x4){pw[4], pw[5], pw[6], pw[7]};
;     }
	global_load_dwordx4 v[0:3], v[64:65], off offset:16
	global_load_dwordx4 v[4:7], v[64:65], off
	global_load_dwordx4 v[12:15], v[64:65], off offset:48
	global_load_dwordx4 v[16:19], v[64:65], off offset:32
	ds_read_b128 v[20:23], v97
	ds_read_b128 v[24:27], v97 offset:32
	ds_read_b128 v[28:31], v97 offset:48
	ds_read_b128 v[32:35], v97 offset:16
	v_mov_b32_e32 v11, v147
	v_mov_b32_e32 v10, v146
	s_waitcnt lgkmcnt(3)
	v_mul_f32_e32 v46, v21, v21
	v_fmac_f32_e32 v46, v20, v20
	v_fmac_f32_e32 v46, v22, v22
	v_fmac_f32_e32 v46, v23, v23
	s_waitcnt lgkmcnt(0)
	v_fmac_f32_e32 v46, v32, v32
	v_fmac_f32_e32 v46, v33, v33
	v_fmac_f32_e32 v46, v34, v34
	v_pk_mul_f32 v[40:41], v[24:25], v[24:25]
	v_fmac_f32_e32 v46, v35, v35
	v_add_f32_e32 v40, v40, v46
	v_pk_mul_f32 v[38:39], v[26:27], v[26:27]
	v_add_f32_e32 v40, v41, v40
	v_add_f32_e32 v38, v38, v40
	v_pk_mul_f32 v[44:45], v[28:29], v[28:29]
	v_add_f32_e32 v38, v39, v38
	v_add_f32_e32 v38, v44, v38
	v_pk_mul_f32 v[42:43], v[30:31], v[30:31]
	v_add_f32_e32 v38, v45, v38
	v_add_f32_e32 v38, v42, v38
	v_add_f32_e32 v38, v43, v38
	ds_bpermute_b32 v39, v98, v38
	v_mov_b32_e32 v9, v144
	v_mov_b32_e32 v8, v145
	s_waitcnt lgkmcnt(0)
	v_add_f32_e32 v38, v38, v39
	ds_bpermute_b32 v39, v99, v38
	s_waitcnt lgkmcnt(0)
	v_add_f32_e32 v40, v38, v39
	ds_bpermute_b32 v41, v100, v40
	v_lshl_add_u64 v[38:39], v[36:37], 0, s[30:31]
	v_add_co_u32_e32 v36, vcc, s41, v36
	s_waitcnt lgkmcnt(0)
	v_add_f32_e32 v40, v40, v41
	v_fmamk_f32 v40, v40, 0x3c000000, v104
	v_mul_f32_e32 v41, 0x4b800000, v40
	v_cmp_gt_f32_e64 s[10:11], s3, v40
	v_addc_co_u32_e32 v37, vcc, 0, v37, vcc
	s_nop 0
	v_cndmask_b32_e64 v40, v40, v41, s[10:11]
	v_rsq_f32_e32 v40, v40
	s_andn2_b64 vcc, exec, s[34:35]
	v_mul_f32_e32 v41, 0x45800000, v40
	v_cndmask_b32_e64 v40, v40, v41, s[10:11]
	v_pk_mul_f32 v[20:21], v[20:21], v[40:41] op_sel_hi:[1,0]
	v_pk_mul_f32 v[22:23], v[22:23], v[40:41] op_sel_hi:[1,0]
	v_pk_mul_f32 v[32:33], v[32:33], v[40:41] op_sel_hi:[1,0]
	v_pk_mul_f32 v[34:35], v[34:35], v[40:41] op_sel_hi:[1,0]
	v_pk_mul_f32 v[24:25], v[24:25], v[40:41] op_sel_hi:[1,0]
	v_pk_mul_f32 v[26:27], v[26:27], v[40:41] op_sel_hi:[1,0]
	v_pk_mul_f32 v[28:29], v[28:29], v[40:41] op_sel_hi:[1,0]
	v_pk_mul_f32 v[30:31], v[30:31], v[40:41] op_sel_hi:[1,0]
	s_waitcnt vmcnt(3)
	v_pk_mul_f32 v[0:1], v[0:1], v[32:33]
	s_waitcnt vmcnt(2)
	v_pk_mul_f32 v[4:5], v[4:5], v[20:21]
	v_pk_mul_f32 v[6:7], v[6:7], v[22:23]
	v_pk_mul_f32 v[2:3], v[2:3], v[34:35]
	s_waitcnt vmcnt(0)
	v_pk_mul_f32 v[16:17], v[16:17], v[24:25]
	v_pk_mul_f32 v[18:19], v[18:19], v[26:27]
	v_pk_mul_f32 v[12:13], v[12:13], v[28:29]
	v_pk_mul_f32 v[14:15], v[14:15], v[30:31]
	v_pk_mul_f32 v[4:5], v[4:5], v[170:171]
	v_pk_mul_f32 v[6:7], v[6:7], v[172:173]
	v_pk_mul_f32 v[20:21], v[0:1], v[48:49]
	v_pk_mul_f32 v[22:23], v[2:3], v[50:51]
	v_pk_mul_f32 v[16:17], v[16:17], v[174:175]
	v_pk_mul_f32 v[18:19], v[18:19], v[52:53]
	v_pk_mul_f32 v[12:13], v[12:13], v[54:55]
	v_pk_mul_f32 v[14:15], v[14:15], v[176:177]
	v_cvt_pk_bf16_f32 v0, v4, v5
	v_cvt_pk_bf16_f32 v1, v6, v7
	v_cvt_pk_bf16_f32 v2, v20, v21
	v_cvt_pk_bf16_f32 v3, v22, v23
	v_cvt_pk_bf16_f32 v4, v16, v17
	v_cvt_pk_bf16_f32 v5, v18, v19
	v_cvt_pk_bf16_f32 v6, v12, v13
	v_cvt_pk_bf16_f32 v7, v14, v15
	global_store_dwordx4 v[36:37], v[0:3], off offset:2048
	global_store_dwordx4 v[38:39], v[4:7], off offset:16
	v_mov_b32_e32 v15, v130
	v_mov_b32_e32 v14, v125
	v_mov_b32_e32 v13, v126
	v_mov_b32_e32 v12, v127
	s_waitcnt vmcnt(2)
	v_perm_b32 v140, v214, v213, s39
	v_perm_b32 v141, v216, v215, s39
	v_perm_b32 v142, v218, v217, s39
	v_perm_b32 v143, v220, v219, s39
	v_perm_b32 v133, v222, v221, s39
	v_perm_b32 v134, v224, v223, s39
	v_perm_b32 v135, v211, v225, s39
	v_perm_b32 v136, v210, v212, s39
	v_mov_b32_e32 v0, v140
	v_mov_b32_e32 v1, v141
	v_mov_b32_e32 v2, v142
	v_mov_b32_e32 v3, v143
	v_mov_b32_e32 v4, v133
	v_mov_b32_e32 v5, v134
	v_mov_b32_e32 v6, v135
	v_mov_b32_e32 v7, v136
	s_barrier
	s_cbranch_vccz .LBB0_739
.LBB0_733:
	s_add_i32 s42, s42, s94
	s_cmpk_gt_i32 s42, 0x7ff
	s_cselect_b64 s[34:35], -1, 0
	s_and_b64 vcc, exec, s[34:35]
	s_cbranch_vccnz .LBB0_735
	s_add_i32 s2, s50, s54
	s_andn2_b32 s2, s2, 63
	v_add_u32_e32 v226, s2, v71
	s_add_i32 s2, s40, s36
	s_and_b32 s2, s2, 0x380
	v_or_b32_e32 v227, s2, v59
	v_lshlrev_b32_e32 v227, 1, v227
	v_lshl_or_b32 v226, v226, 11, v227
	v_add_u32_e32 v228, 0x1000, v226
	v_add_u32_e32 v229, 0x2000, v226
	v_add_u32_e32 v230, 0x3000, v226
	v_add_u32_e32 v231, 0x4000, v226
	v_add_u32_e32 v232, 0x5000, v226
	v_add_u32_e32 v233, 0x6000, v226
	v_add_u32_e32 v234, 0x7000, v226
	global_load_ushort v114, v226, s[16:17]
	global_load_ushort v105, v226, s[14:15]
	global_load_ushort v213, v226, s[18:19]
	global_load_ushort v112, v226, s[16:17] offset:2048
	global_load_ushort v106, v226, s[14:15] offset:2048
	global_load_ushort v214, v226, s[18:19] offset:2048
	global_load_ushort v113, v228, s[16:17]
	global_load_ushort v107, v228, s[14:15]
	global_load_ushort v215, v228, s[18:19]
	global_load_ushort v122, v228, s[16:17] offset:2048
	global_load_ushort v108, v228, s[14:15] offset:2048
	global_load_ushort v216, v228, s[18:19] offset:2048
	global_load_ushort v123, v229, s[16:17]
	global_load_ushort v109, v229, s[14:15]
	global_load_ushort v217, v229, s[18:19]
	global_load_ushort v124, v229, s[16:17] offset:2048
	global_load_ushort v116, v229, s[14:15] offset:2048
	global_load_ushort v218, v229, s[18:19] offset:2048
	global_load_ushort v128, v230, s[16:17]
	global_load_ushort v110, v230, s[14:15]
	global_load_ushort v219, v230, s[18:19]
	global_load_ushort v129, v230, s[16:17] offset:2048
	global_load_ushort v111, v230, s[14:15] offset:2048
	global_load_ushort v220, v230, s[18:19] offset:2048
	global_load_ushort v137, v231, s[16:17]
	global_load_ushort v118, v231, s[14:15]
	global_load_ushort v221, v231, s[18:19]
	global_load_ushort v138, v231, s[16:17] offset:2048
	global_load_ushort v120, v231, s[14:15] offset:2048
	global_load_ushort v222, v231, s[18:19] offset:2048
	global_load_ushort v139, v232, s[16:17]
	global_load_ushort v117, v232, s[14:15]
	global_load_ushort v223, v232, s[18:19]
	global_load_ushort v224, v232, s[18:19] offset:2048
	global_load_ushort v225, v233, s[18:19]
	global_load_ushort v125, v233, s[14:15] offset:2048
	global_load_ushort v211, v233, s[18:19] offset:2048
	global_load_ushort v144, v234, s[16:17]
	global_load_ushort v126, v234, s[14:15]
	global_load_ushort v212, v234, s[18:19]
	global_load_ushort v145, v234, s[16:17] offset:2048
	global_load_ushort v127, v234, s[14:15] offset:2048
	global_load_ushort v210, v234, s[18:19] offset:2048
	global_load_ushort v148, v232, s[16:17] offset:2048
	global_load_ushort v131, v232, s[14:15] offset:2048
	global_load_ushort v147, v233, s[16:17]
	global_load_ushort v130, v233, s[14:15]
	global_load_ushort v146, v233, s[16:17] offset:2048
	s_branch .LBB0_736
